# grid barrier 2: workgroups vb<136 (P2b GEMM tiles, no dependence on P2a outputs) arrive without waiting
# speedup vs baseline: 1.0260x; 1.0050x over previous
; __device__ __forceinline__ unsigned xb_ld(unsigned* p)              { return __hip_atomic_load(p, __ATOMIC_RELAXED, __HIP_MEMORY_SCOPE_AGENT); }
; __device__ __forceinline__ unsigned xb_add(unsigned* p, unsigned v) { return __hip_atomic_fetch_add(p, v, __ATOMIC_RELAXED, __HIP_MEMORY_SCOPE_AGENT); }
; #define XB_SPIN(cond, bar) do { unsigned _sp = 0; while (cond) { __builtin_amdgcn_s_sleep(1); \
;     if ((++_sp & 255u) == 0u) { if (xb_ld(&(bar)[XB_TMO])) break; if (_sp > XB_SPIN_CAP) { atomicAdd(&(bar)[XB_TMO], 1u); break; } } } } while (0)
; #define GRID_SYNC() xcd_barrier(gbar)
; __device__ __forceinline__ void xcd_barrier(const XcdBarrier& b) {
;     ...
;         if (nloc == 0u) { unsigned uni; xcd_barrier_complete(bar, b.x, nloc, nx, uni); b.st[0] = nloc; b.st[1] = nx; b.st[2] = uni; }
;         const unsigned old = xb_add(&bar[XB_XSUB(b.x)], 1u);
;         const unsigned gen = old / nloc;
;         if (old + 1u == (gen + 1u) * nloc) {
;             __builtin_amdgcn_fence(__ATOMIC_RELEASE, "agent");
;             asm volatile("s_waitcnt vmcnt(0)" ::: "memory");
;             const unsigned og = xb_add(&bar[XB_TOP], 1u);
;             const unsigned tg = og / nx;
;             if (og + 1u == (tg + 1u) * nx) xb_add(&bar[XB_TOPGEN], 1u);
;             else XB_SPIN(xb_ld(&bar[XB_TOPGEN]) == tg, bar);
;             __builtin_amdgcn_fence(__ATOMIC_ACQUIRE, "agent");
;             xb_add(&bar[XB_XGEN(b.x)], 1u);
;             asm volatile("s_waitcnt vmcnt(0)" ::: "memory");
;         } else {
;             XB_SPIN(xb_ld(&bar[XB_XGEN(b.x)]) == gen, bar);
; __global__ void __launch_bounds__(512, 2) fwd_kernel(Args args) {
;     ...
;             GRID_SYNC();
.LBB0_400:
	s_or_b64 exec, exec, s[8:9]
	v_cvt_f32_u32_e32 v4, v2
	s_waitcnt vmcnt(0)
	v_readfirstlane_b32 s3, v3
	v_sub_u32_e32 v3, 0, v2
	v_rcp_iflag_f32_e32 v4, v4
	v_add_u32_e32 v5, s3, v1
	v_mul_f32_e32 v4, 0x4f7ffffe, v4
	v_cvt_u32_f32_e32 v4, v4
	v_mul_lo_u32 v1, v3, v4
	v_mul_hi_u32 v1, v4, v1
	v_add_u32_e32 v1, v4, v1
	v_mul_hi_u32 v1, v5, v1
	v_mul_lo_u32 v3, v1, v2
	v_sub_u32_e32 v3, v5, v3
	v_add_u32_e32 v4, 1, v1
	v_cmp_ge_u32_e32 vcc, v3, v2
	s_nop 1
	v_cndmask_b32_e32 v1, v1, v4, vcc
	v_sub_u32_e32 v4, v3, v2
	v_cndmask_b32_e32 v3, v3, v4, vcc
	v_add_u32_e32 v4, 1, v1
	v_cmp_ge_u32_e32 vcc, v3, v2
	v_add_u32_e32 v3, 1, v5
	s_nop 0
	v_cndmask_b32_e32 v1, v1, v4, vcc
	v_mul_lo_u32 v4, v2, v1
	v_add_u32_e32 v2, v4, v2
	v_cmp_ne_u32_e32 vcc, v3, v2
	s_and_saveexec_b64 s[6:7], vcc
	s_xor_b64 s[6:7], exec, s[6:7]
	s_cbranch_execz .LBB0_416
	s_cmpk_lt_i32 s2, 0x88
	s_cbranch_scc1 .LBB0_416
	s_waitcnt lgkmcnt(0)
	v_mov_b32_e32 v0, 0x2000
	global_load_dword v0, v0, s[4:5] offset:1024 sc1
	s_add_u32 s12, s4, 0x2400
	s_addc_u32 s13, s5, 0
	s_waitcnt vmcnt(0)
	v_cmp_eq_u32_e32 vcc, v0, v1
	s_and_saveexec_b64 s[8:9], vcc
	s_cbranch_execz .LBB0_415
	s_add_u32 s10, s26, 0xc200
	s_addc_u32 s11, s27, 0
	s_mov_b32 s3, 1
	s_mov_b64 s[14:15], 0
	v_mov_b32_e32 v0, 0
	s_branch .LBB0_404
